# idx units: zigzag query-block assignment for even per-CU causal length
# baseline (speedup 1.0000x reference)
; __device__ __forceinline__ void idx_unit(unsigned char* lds, const bf16_t* P, int b, int qb16, unsigned* bits) {
;     int tid_o = threadIdx.x; asm volatile("" : "+v"(tid_o));
;     const int tid = tid_o, lane = tid & 63, wid = __builtin_amdgcn_readfirstlane(tid >> 6), r32 = lane & 31, hi = lane >> 5;
;     unsigned short* sc = (unsigned short*)lds;
;     float* wl = (float*)(lds + 131072);
;     const int t0 = qb16 * 16; const size_t tokb = (size_t)b * SEQ, tok0 = tokb + t0;
;     const int nscan = ((t0 + 16 + 511) >> 9) << 9;
;     const int ncomp = ((t0 + 16 + 31) / 32);
;     const int nblk = ncomp;
;     if (tid < 128) wl[tid] = bf2f(P[(tok0 + (tid >> 3)) * PW + P_IW + (tid & 7)]) * (0.35355339059327373f * 0.125f);
; __global__ void __launch_bounds__(512, 2) fwd_kernel(Args a) {
;     ...
;         for (int it = cb_; it < 4096; it += G) idx_unit(lds, P, it & 15, it >> 4, BITS);
.LBB0_394:
	s_bfe_u32 s0, s76, 0x10008
	s_sub_u32 s0, 0, s0
	s_and_b32 s0, s0, 0xf0
	s_xor_b32 s1, s76, s0
	s_and_b32 s8, s1, -16
	s_lshl_b32 s0, s1, 12
	s_and_b32 s64, s0, 0xf000
	s_ashr_i32 s0, s8, 31
	s_add_u32 s70, s64, s8
	v_mov_b32_e32 v182, v228
	s_addc_u32 s71, 0, s0
	s_movk_i32 s0, 0x80
	s_nop 0
	v_readfirstlane_b32 s4, v182
	v_cmp_gt_i32_e32 vcc, s0, v182
	s_and_saveexec_b64 s[0:1], vcc
	s_cbranch_execz .LBB0_396
	v_ashrrev_i32_e32 v2, 3, v182
	v_ashrrev_i32_e32 v3, 31, v2
	v_lshl_add_u64 v[2:3], s[70:71], 0, v[2:3]
	v_mov_b64_e32 v[4:5], s[46:47]
	v_and_b32_e32 v0, 7, v182
	v_mad_u64_u32 v[4:5], s[6:7], v2, s37, v[4:5]
	v_mad_i32_i24 v5, v3, s37, v5
	v_lshlrev_b32_e32 v0, 1, v0
	v_lshl_add_u64 v[2:3], v[4:5], 0, v[0:1]
	v_add_co_u32_e32 v2, vcc, 0x1000, v2
	s_nop 1
	v_addc_co_u32_e32 v3, vcc, 0, v3, vcc
	global_load_ushort v0, v[2:3], off offset:1152
	v_lshl_add_u32 v2, v182, 2, 0
	v_add_u32_e32 v2, 0x20000, v2
	s_waitcnt vmcnt(0)
	v_lshlrev_b32_e32 v0, 16, v0
	v_mul_f32_e32 v0, 0x3d3504f3, v0
	ds_write_b32 v2, v0
